# latent attention loop: K/V prefetch loads made unconditional, vmcnt waits counted exactly (+16)
# speedup vs baseline: 1.0492x; 1.0492x over previous
.LBB0_847:
	s_add_i32 s62, s20, -4
	s_cmp_lt_u32 s62, 30
	s_cselect_b64 s[24:25], -1, 0
	s_cmp_gt_u32 s62, 29
	s_add_u32 s10, s61, s20
	s_addc_u32 s11, 0, s21
	s_add_u32 s63, s10, 0xffffffe6
	s_addc_u32 s64, s11, -1
	s_add_u32 s65, s20, -2
	s_addc_u32 s66, s21, -1
	s_cmp_lt_u32 s62, 14
	s_cselect_b64 vcc, -1, 0
	s_and_b64 s[10:11], vcc, exec
	s_cselect_b32 s11, s66, s64
	s_cselect_b32 s10, s65, s63
	v_cndmask_b32_e32 v1, v219, v215, vcc
	v_cndmask_b32_e32 v0, v218, v214, vcc
	s_lshl_b64 s[10:11], s[10:11], 12
	v_cndmask_b32_e32 v7, v221, v217, vcc
	v_cndmask_b32_e32 v6, v220, v216, vcc
	v_lshl_add_u64 v[0:1], v[0:1], 0, s[10:11]
	v_lshl_add_u64 v[6:7], v[6:7], 0, s[10:11]
	global_load_dwordx4 v[160:163], v[0:1], off
	global_load_dwordx4 v[164:167], v[0:1], off offset:1024
	global_load_dwordx4 v[172:175], v[6:7], off
	global_load_dwordx4 v[176:179], v[6:7], off offset:1024
	global_load_dwordx4 v[168:171], v[0:1], off offset:2048
	global_load_dwordx4 v[180:183], v[0:1], off offset:3072
	global_load_dwordx4 v[184:187], v[6:7], off offset:2048
	global_load_dwordx4 v[188:191], v[6:7], off offset:3072
.LBB0_849:
	s_cmp_gt_u32 s62, 15
	s_mov_b64 s[10:11], -1
	s_cbranch_scc0 .LBB0_979
	s_sub_i32 s10, s20, 20
	s_lshr_b32 s10, s10, 1
	s_and_b32 s11, s62, 1
	s_add_i32 s10, s10, s60
	v_lshl_or_b32 v0, s11, 5, v198
	s_mulk_i32 s10, 0x7c
	s_add_i32 s10, s15, s10
	v_sub_u32_e32 v1, v0, v193
	v_lshl_add_u32 v5, v1, 2, s10
	s_cmp_lg_u32 s11, s47
	v_sub_u32_e32 v6, v0, v223
	s_mov_b64 s[10:11], -1
	s_cbranch_scc0 .LBB0_875
	s_and_b64 vcc, exec, s[6:7]
	s_cbranch_vccz .LBB0_863
	s_waitcnt vmcnt(23)
	v_mfma_f32_32x32x16_bf16 v[48:63], v[96:99], v[80:83], 0
	v_add_u32_e32 v0, 24, v6
	v_cmp_gt_u32_e32 vcc, 16, v0
	v_mov_b32_e32 v0, 0xf149f2ca
	v_mov_b32_e32 v1, 0xf149f2ca
	s_waitcnt vmcnt(22)
	v_mfma_f32_32x32x16_bf16 v[48:63], v[100:103], v[84:87], v[48:63]
	s_waitcnt vmcnt(19)
	v_mfma_f32_32x32x16_bf16 v[48:63], v[112:115], v[88:91], v[48:63]
	s_waitcnt vmcnt(18)
	v_mfma_f32_32x32x16_bf16 v[48:63], v[116:119], v[92:95], v[48:63]
	s_and_saveexec_b64 s[10:11], vcc
	s_cbranch_execz .LBB0_854
	ds_read_b32 v1, v5 offset:2048
	s_waitcnt lgkmcnt(0)
	s_nop 7
	v_fmac_f32_e32 v1, 0x3e38aa3b, v60

.LBB0_862:
	v_sub_f32_e32 v1, v1, v9
	v_sub_f32_e32 v0, v0, v9
	v_exp_f32_e32 v1, v1
	v_exp_f32_e32 v0, v0
	v_sub_f32_e32 v7, v7, v9
	v_exp_f32_e32 v7, v7
	v_sub_f32_e32 v3, v3, v9
	v_exp_f32_e32 v3, v3
	v_cvt_pk_bf16_f32 v12, v1, v0
	v_add_f32_e32 v1, 0, v1
	v_add_f32_e32 v0, v0, v1
	v_add_f32_e32 v0, v7, v0
	v_cvt_pk_bf16_f32 v13, v7, v3
	v_mov_b32_e32 v10, v2
	v_mov_b32_e32 v11, v2
	v_add_f32_e32 v0, v3, v0
	v_add_f32_e32 v209, v0, v8
	v_mfma_f32_32x32x16_bf16 v[48:63], v[108:111], v[10:13], v[48:63]
	s_mov_b64 s[10:11], 0
	s_waitcnt vmcnt(16)
	v_mfma_f32_32x32x16_bf16 v[64:79], v[128:131], v[10:13], v[64:79]
.LBB0_863:
	s_and_b64 vcc, exec, s[10:11]
	s_cbranch_vccz .LBB0_1054
	s_waitcnt vmcnt(23)
	v_mfma_f32_32x32x16_bf16 v[48:63], v[96:99], v[80:83], 0
	v_cmp_gt_u32_e32 vcc, 16, v6
	v_mov_b32_e32 v1, 0xf149f2ca
	v_mov_b32_e32 v0, 0xf149f2ca
	s_waitcnt vmcnt(22)
	v_mfma_f32_32x32x16_bf16 v[48:63], v[100:103], v[84:87], v[48:63]
	s_waitcnt vmcnt(19)
	v_mfma_f32_32x32x16_bf16 v[48:63], v[112:115], v[88:91], v[48:63]
	s_waitcnt vmcnt(18)
	v_mfma_f32_32x32x16_bf16 v[48:63], v[116:119], v[92:95], v[48:63]
	s_and_saveexec_b64 s[10:11], vcc
	s_cbranch_execz .LBB0_866
	ds_read_b32 v0, v5 offset:1952
	s_waitcnt lgkmcnt(0)
	s_nop 7
	v_fmac_f32_e32 v0, 0x3e38aa3b, v48

.LBB0_874:
	v_sub_f32_e32 v1, v1, v9
	v_sub_f32_e32 v0, v0, v9
	v_sub_f32_e32 v7, v7, v9
	v_sub_f32_e32 v3, v3, v9
	v_exp_f32_e32 v10, v1
	v_exp_f32_e32 v9, v0
	v_exp_f32_e32 v11, v3
	v_exp_f32_e32 v7, v7
	v_mov_b32_e32 v3, v2
	v_cvt_pk_bf16_f32 v0, v9, v10
	v_add_f32_e32 v9, 0, v9
	v_add_f32_e32 v9, v10, v9
	v_add_f32_e32 v9, v11, v9
	v_cvt_pk_bf16_f32 v1, v11, v7
	v_add_f32_e32 v7, v7, v9
	v_add_f32_e32 v209, v7, v8
	v_mfma_f32_32x32x16_bf16 v[48:63], v[104:107], v[0:3], v[48:63]
	s_mov_b64 s[10:11], 0
	s_waitcnt vmcnt(17)
	v_mfma_f32_32x32x16_bf16 v[64:79], v[120:123], v[0:3], v[64:79]

.LBB0_876:
	s_waitcnt vmcnt(23)
	v_mfma_f32_32x32x16_bf16 v[48:63], v[96:99], v[80:83], 0
	v_cmp_gt_u32_e32 vcc, 16, v6
	v_mov_b32_e32 v0, 0xf149f2ca
	v_mov_b32_e32 v1, 0xf149f2ca
	s_waitcnt vmcnt(22)
	v_mfma_f32_32x32x16_bf16 v[48:63], v[100:103], v[84:87], v[48:63]
	s_waitcnt vmcnt(19)
	v_mfma_f32_32x32x16_bf16 v[48:63], v[112:115], v[88:91], v[48:63]
	s_waitcnt vmcnt(18)
	v_mfma_f32_32x32x16_bf16 v[48:63], v[116:119], v[92:95], v[48:63]
	s_and_saveexec_b64 s[10:11], vcc
	s_cbranch_execz .LBB0_878
	ds_read_b32 v1, v5 offset:1952
	s_waitcnt lgkmcnt(0)
	s_nop 7
	v_fmac_f32_e32 v1, 0x3e38aa3b, v48

.LBB0_910:
	v_sub_f32_e32 v1, v1, v6
	v_exp_f32_e32 v1, v1
	v_sub_f32_e32 v0, v0, v6
	v_exp_f32_e32 v0, v0
	v_sub_f32_e32 v7, v7, v6
	v_exp_f32_e32 v7, v7
	v_sub_f32_e32 v3, v3, v6
	v_exp_f32_e32 v3, v3
	v_sub_f32_e32 v9, v9, v6
	v_add_f32_e32 v228, 0, v1
	v_exp_f32_e32 v229, v9
	v_sub_f32_e32 v8, v8, v6
	v_add_f32_e32 v228, v0, v228
	v_exp_f32_e32 v230, v8
	v_sub_f32_e32 v9, v11, v6
	v_add_f32_e32 v8, v7, v228
	v_exp_f32_e32 v11, v9
	v_sub_f32_e32 v9, v10, v6
	v_add_f32_e32 v8, v3, v8
	v_exp_f32_e32 v228, v9
	v_sub_f32_e32 v9, v14, v6
	v_add_f32_e32 v8, v229, v8
	v_exp_f32_e32 v14, v9
	v_sub_f32_e32 v9, v13, v6
	v_add_f32_e32 v8, v230, v8
	v_exp_f32_e32 v13, v9
	v_add_f32_e32 v8, v11, v8
	v_add_f32_e32 v8, v228, v8
	v_add_f32_e32 v8, v14, v8
	v_add_f32_e32 v231, v13, v8
	v_sub_f32_e32 v8, v213, v6
	v_exp_f32_e32 v213, v8
	v_cvt_pk_bf16_f32 v8, v1, v0
	v_cvt_pk_bf16_f32 v9, v7, v3
	v_cvt_pk_bf16_f32 v10, v229, v230
	v_cvt_pk_bf16_f32 v11, v11, v228
	v_sub_f32_e32 v0, v12, v6
	v_sub_f32_e32 v1, v209, v6
	v_mfma_f32_32x32x16_bf16 v[48:63], v[104:107], v[8:11], v[48:63]
	v_sub_f32_e32 v3, v15, v6
	v_sub_f32_e32 v7, v227, v6
	v_sub_f32_e32 v6, v226, v6
	v_exp_f32_e32 v0, v0
	v_exp_f32_e32 v1, v1
	v_exp_f32_e32 v3, v3
	v_add_f32_e32 v12, v213, v231
	s_waitcnt vmcnt(17)
	v_mfma_f32_32x32x16_bf16 v[64:79], v[120:123], v[8:11], v[64:79]
	v_exp_f32_e32 v10, v7
	v_exp_f32_e32 v11, v6
	v_cvt_pk_bf16_f32 v6, v14, v13
	v_cvt_pk_bf16_f32 v7, v213, v0
	v_cvt_pk_bf16_f32 v8, v1, v3
	v_cvt_pk_bf16_f32 v9, v10, v11
	v_add_f32_e32 v0, v0, v12
	v_add_f32_e32 v0, v1, v0
	v_mfma_f32_32x32x16_bf16 v[48:63], v[108:111], v[6:9], v[48:63]
	v_add_f32_e32 v0, v3, v0
	v_add_f32_e32 v0, v10, v0
	v_add_f32_e32 v0, v11, v0
	v_add_f32_e32 v209, v0, v5
	s_waitcnt vmcnt(16)
	v_mfma_f32_32x32x16_bf16 v[64:79], v[128:131], v[6:9], v[64:79]

.LBB0_912:
	s_cmp_gt_u32 s62, 28
.LBB0_913:
	s_add_u32 s63, s20, -1
	s_addc_u32 s64, s21, -1
	s_add_u32 s10, s61, s20
	s_addc_u32 s11, 0, s21
	s_add_u32 s65, s10, 0xffffffe7
	s_addc_u32 s66, s11, -1
	s_cmp_lt_u32 s62, 13
	s_cselect_b64 vcc, -1, 0
	s_and_b64 s[10:11], vcc, exec
	s_cselect_b32 s11, s64, s66
	s_cselect_b32 s10, s63, s65
	v_cndmask_b32_e32 v1, v219, v215, vcc
	v_cndmask_b32_e32 v0, v218, v214, vcc
	s_lshl_b64 s[10:11], s[10:11], 12
	v_cndmask_b32_e32 v5, v221, v217, vcc
	v_cndmask_b32_e32 v4, v220, v216, vcc
	v_lshl_add_u64 v[0:1], v[0:1], 0, s[10:11]
	v_lshl_add_u64 v[4:5], v[4:5], 0, s[10:11]
	global_load_dwordx4 v[96:99], v[0:1], off
	global_load_dwordx4 v[100:103], v[0:1], off offset:1024
	global_load_dwordx4 v[104:107], v[4:5], off
	global_load_dwordx4 v[108:111], v[4:5], off offset:1024
	global_load_dwordx4 v[112:115], v[0:1], off offset:2048
	global_load_dwordx4 v[116:119], v[0:1], off offset:3072
	global_load_dwordx4 v[120:123], v[4:5], off offset:2048
	global_load_dwordx4 v[128:131], v[4:5], off offset:3072
.LBB0_914:
	s_cmp_gt_u32 s62, 14
	s_mov_b64 s[10:11], -1
	s_cbranch_scc0 .LBB0_983
	s_sub_i32 s10, s20, 19
	s_and_b32 s11, s10, 1
	s_lshr_b32 s10, s10, 1
	s_add_i32 s10, s10, s60
	v_lshl_or_b32 v0, s11, 5, v198
	s_mulk_i32 s10, 0x7c
	s_add_i32 s10, s15, s10
	v_sub_u32_e32 v1, v0, v193
	v_lshl_add_u32 v213, v1, 2, s10
	s_cmp_lg_u32 s11, s47
	v_sub_u32_e32 v226, v0, v223
	s_mov_b64 s[10:11], -1
	s_cbranch_scc0 .LBB0_940
	s_and_b64 vcc, exec, s[6:7]
	s_cbranch_vccz .LBB0_928
	s_waitcnt vmcnt(23)
	v_mfma_f32_32x32x16_bf16 v[4:19], v[124:127], v[80:83], 0
	v_add_u32_e32 v0, 24, v226
	v_cmp_gt_u32_e32 vcc, 16, v0
	v_mov_b32_e32 v0, 0xf149f2ca
	v_mov_b32_e32 v1, 0xf149f2ca
	s_waitcnt vmcnt(21)
	v_mfma_f32_32x32x16_bf16 v[4:19], v[136:139], v[84:87], v[4:19]
	s_waitcnt vmcnt(19)
	v_mfma_f32_32x32x16_bf16 v[4:19], v[144:147], v[88:91], v[4:19]
	s_waitcnt vmcnt(18)
	v_mfma_f32_32x32x16_bf16 v[4:19], v[148:151], v[92:95], v[4:19]
	s_and_saveexec_b64 s[10:11], vcc
	s_cbranch_execz .LBB0_919
	ds_read_b32 v1, v213 offset:2048
	s_waitcnt lgkmcnt(0)
	s_nop 7
	v_fmac_f32_e32 v1, 0x3e38aa3b, v16

.LBB0_927:
	v_sub_f32_e32 v1, v1, v7
	v_sub_f32_e32 v0, v0, v7
	v_exp_f32_e32 v1, v1
	v_exp_f32_e32 v0, v0
	v_sub_f32_e32 v5, v5, v7
	v_exp_f32_e32 v5, v5
	v_sub_f32_e32 v3, v3, v7
	v_exp_f32_e32 v3, v3
	v_cvt_pk_bf16_f32 v10, v1, v0
	v_add_f32_e32 v1, 0, v1
	v_add_f32_e32 v0, v0, v1
	v_add_f32_e32 v0, v5, v0
	v_cvt_pk_bf16_f32 v11, v5, v3
	v_mov_b32_e32 v8, v2
	v_mov_b32_e32 v9, v2
	v_add_f32_e32 v0, v3, v0
	v_add_f32_e32 v201, v0, v6
	v_mfma_f32_32x32x16_bf16 v[16:31], v[140:143], v[8:11], v[16:31]
	s_mov_b64 s[10:11], 0
	s_waitcnt vmcnt(16)
	v_mfma_f32_32x32x16_bf16 v[32:47], v[156:159], v[8:11], v[32:47]
.LBB0_928:
	s_and_b64 vcc, exec, s[10:11]
	s_cbranch_vccz .LBB0_1055
	s_waitcnt vmcnt(23)
	v_mfma_f32_32x32x16_bf16 v[4:19], v[124:127], v[80:83], 0
	v_cmp_gt_u32_e32 vcc, 16, v226
	v_mov_b32_e32 v1, 0xf149f2ca
	v_mov_b32_e32 v0, 0xf149f2ca
	s_waitcnt vmcnt(21)
	v_mfma_f32_32x32x16_bf16 v[4:19], v[136:139], v[84:87], v[4:19]
	s_waitcnt vmcnt(19)
	v_mfma_f32_32x32x16_bf16 v[4:19], v[144:147], v[88:91], v[4:19]
	s_waitcnt vmcnt(18)
	v_mfma_f32_32x32x16_bf16 v[4:19], v[148:151], v[92:95], v[4:19]
	s_and_saveexec_b64 s[10:11], vcc
	s_cbranch_execz .LBB0_931
	ds_read_b32 v0, v213 offset:1952
	s_waitcnt lgkmcnt(0)
	s_nop 7
	v_fmac_f32_e32 v0, 0x3e38aa3b, v4

.LBB0_939:
	v_sub_f32_e32 v1, v1, v7
	v_sub_f32_e32 v0, v0, v7
	v_sub_f32_e32 v5, v5, v7
	v_sub_f32_e32 v3, v3, v7
	v_exp_f32_e32 v8, v1
	v_exp_f32_e32 v7, v0
	v_exp_f32_e32 v9, v3
	v_exp_f32_e32 v5, v5
	v_mov_b32_e32 v3, v2
	v_cvt_pk_bf16_f32 v0, v7, v8
	v_add_f32_e32 v7, 0, v7
	v_add_f32_e32 v7, v8, v7
	v_add_f32_e32 v7, v9, v7
	v_cvt_pk_bf16_f32 v1, v9, v5
	v_add_f32_e32 v5, v5, v7
	v_add_f32_e32 v201, v5, v6
	v_mfma_f32_32x32x16_bf16 v[16:31], v[132:135], v[0:3], v[16:31]
	s_mov_b64 s[10:11], 0
	s_waitcnt vmcnt(17)
	v_mfma_f32_32x32x16_bf16 v[32:47], v[152:155], v[0:3], v[32:47]

.LBB0_941:
	s_waitcnt vmcnt(23)
	v_mfma_f32_32x32x16_bf16 v[4:19], v[124:127], v[80:83], 0
	v_cmp_gt_u32_e32 vcc, 16, v226
	v_mov_b32_e32 v0, 0xf149f2ca
	v_mov_b32_e32 v1, 0xf149f2ca
	s_waitcnt vmcnt(21)
	v_mfma_f32_32x32x16_bf16 v[4:19], v[136:139], v[84:87], v[4:19]
	s_waitcnt vmcnt(19)
	v_mfma_f32_32x32x16_bf16 v[4:19], v[144:147], v[88:91], v[4:19]
	s_waitcnt vmcnt(18)
	v_mfma_f32_32x32x16_bf16 v[4:19], v[148:151], v[92:95], v[4:19]
	s_and_saveexec_b64 s[10:11], vcc
	s_cbranch_execz .LBB0_943
	ds_read_b32 v1, v213 offset:1952
	s_waitcnt lgkmcnt(0)
	s_nop 7
	v_fmac_f32_e32 v1, 0x3e38aa3b, v4

.LBB0_975:
	v_sub_f32_e32 v1, v1, v226
	v_exp_f32_e32 v1, v1
	v_sub_f32_e32 v0, v0, v226
	v_exp_f32_e32 v0, v0
	v_sub_f32_e32 v5, v5, v226
	v_exp_f32_e32 v5, v5
	v_sub_f32_e32 v3, v3, v226
	v_exp_f32_e32 v3, v3
	v_sub_f32_e32 v7, v7, v226
	v_add_f32_e32 v228, 0, v1
	v_exp_f32_e32 v229, v7
	v_sub_f32_e32 v6, v6, v226
	v_add_f32_e32 v228, v0, v228
	v_exp_f32_e32 v230, v6
	v_sub_f32_e32 v7, v9, v226
	v_add_f32_e32 v6, v5, v228
	v_exp_f32_e32 v9, v7
	v_sub_f32_e32 v7, v8, v226
	v_add_f32_e32 v6, v3, v6
	v_exp_f32_e32 v228, v7
	v_sub_f32_e32 v7, v201, v226
	v_add_f32_e32 v6, v229, v6
	v_exp_f32_e32 v201, v7
	v_sub_f32_e32 v7, v11, v226
	v_add_f32_e32 v6, v230, v6
	v_exp_f32_e32 v11, v7
	v_add_f32_e32 v6, v9, v6
	v_add_f32_e32 v6, v228, v6
	v_add_f32_e32 v6, v201, v6
	v_add_f32_e32 v231, v11, v6
	v_sub_f32_e32 v6, v227, v226
	v_exp_f32_e32 v227, v6
	v_cvt_pk_bf16_f32 v6, v1, v0
	v_cvt_pk_bf16_f32 v7, v5, v3
	v_cvt_pk_bf16_f32 v8, v229, v230
	v_cvt_pk_bf16_f32 v9, v9, v228
	v_sub_f32_e32 v0, v10, v226
	v_sub_f32_e32 v1, v13, v226
	v_mfma_f32_32x32x16_bf16 v[16:31], v[132:135], v[6:9], v[16:31]
	v_sub_f32_e32 v3, v12, v226
	v_sub_f32_e32 v5, v15, v226
	v_exp_f32_e32 v0, v0
	v_exp_f32_e32 v1, v1
	v_exp_f32_e32 v3, v3
	v_exp_f32_e32 v5, v5
	s_waitcnt vmcnt(17)
	v_mfma_f32_32x32x16_bf16 v[32:47], v[152:155], v[6:9], v[32:47]
	v_sub_f32_e32 v6, v14, v226
	v_exp_f32_e32 v10, v6
	v_cvt_pk_bf16_f32 v6, v201, v11
	v_cvt_pk_bf16_f32 v7, v227, v0
	v_cvt_pk_bf16_f32 v8, v1, v3
	v_cvt_pk_bf16_f32 v9, v5, v10
	v_add_f32_e32 v11, v227, v231
	v_add_f32_e32 v0, v0, v11
	v_mfma_f32_32x32x16_bf16 v[16:31], v[140:143], v[6:9], v[16:31]
	v_add_f32_e32 v0, v1, v0
	v_add_f32_e32 v0, v3, v0
	v_add_f32_e32 v0, v5, v0
	v_add_f32_e32 v0, v10, v0
	v_add_f32_e32 v201, v0, v213
	s_waitcnt vmcnt(16)
	v_mfma_f32_32x32x16_bf16 v[32:47], v[156:159], v[6:9], v[32:47]

.LBB0_977:
	s_cmp_gt_u32 s62, 27
.LBB0_978:
	s_add_u32 s10, s61, s20
	s_addc_u32 s11, 0, s21
	s_add_u32 s63, s10, 0xffffffe8
	s_addc_u32 s64, s11, -1
	s_cmp_lt_u32 s62, 12
	s_cselect_b64 vcc, -1, 0
	s_and_b64 s[10:11], vcc, exec
	s_cselect_b32 s11, s21, s64
	s_cselect_b32 s10, s20, s63
	v_cndmask_b32_e32 v1, v219, v215, vcc
	v_cndmask_b32_e32 v0, v218, v214, vcc
	s_lshl_b64 s[10:11], s[10:11], 12
	v_cndmask_b32_e32 v7, v221, v217, vcc
	v_cndmask_b32_e32 v6, v220, v216, vcc
	v_lshl_add_u64 v[0:1], v[0:1], 0, s[10:11]
	v_lshl_add_u64 v[6:7], v[6:7], 0, s[10:11]
	global_load_dwordx4 v[124:127], v[0:1], off
	global_load_dwordx4 v[136:139], v[0:1], off offset:1024
	global_load_dwordx4 v[132:135], v[6:7], off
	global_load_dwordx4 v[140:143], v[6:7], off offset:1024
	global_load_dwordx4 v[144:147], v[0:1], off offset:2048
	global_load_dwordx4 v[148:151], v[0:1], off offset:3072
	global_load_dwordx4 v[152:155], v[6:7], off offset:2048
	global_load_dwordx4 v[156:159], v[6:7], off offset:3072
	s_andn2_b64 vcc, exec, s[24:25]
	s_cbranch_vccnz .LBB0_846
	s_branch .LBB0_988

.LBB0_980:
	s_waitcnt vmcnt(23)
	v_mfma_f32_32x32x16_bf16 v[48:63], v[96:99], v[80:83], 0
	s_waitcnt vmcnt(22)
	v_mfma_f32_32x32x16_bf16 v[48:63], v[100:103], v[84:87], v[48:63]
	s_waitcnt vmcnt(19)
	v_mfma_f32_32x32x16_bf16 v[48:63], v[112:115], v[88:91], v[48:63]
	s_waitcnt vmcnt(18)
	v_mfma_f32_32x32x16_bf16 v[48:63], v[116:119], v[92:95], v[48:63]
	s_nop 11
	v_max_f32_e32 v0, v49, v49
	v_max_f32_e32 v1, v48, v48
	v_max_f32_e32 v0, v1, v0
	v_max3_f32 v0, v0, v50, v51
	v_max3_f32 v0, v0, v52, v53
	v_max3_f32 v0, v0, v54, v55
	v_max3_f32 v0, v0, v56, v57
	v_max3_f32 v0, v0, v58, v59
	v_max3_f32 v0, v0, v60, v61
	v_max3_f32 v0, v0, v62, v63
	v_mul_f32_e32 v0, 0x3e38aa3b, v0
	ds_bpermute_b32 v1, v224, v0
	s_waitcnt lgkmcnt(0)
	v_max3_f32 v0, v4, v0, v1
	v_cmp_gt_f32_e32 vcc, v0, v4
	s_cbranch_vccz .LBB0_982
	v_sub_f32_e32 v1, v4, v0
	v_exp_f32_e32 v4, v1
	s_nop 0
	v_mul_f32_e32 v201, v201, v4
	v_pk_mul_f32 v[30:31], v[30:31], v[4:5] op_sel_hi:[1,0]
	v_pk_mul_f32 v[28:29], v[28:29], v[4:5] op_sel_hi:[1,0]
	v_pk_mul_f32 v[26:27], v[26:27], v[4:5] op_sel_hi:[1,0]
	v_pk_mul_f32 v[24:25], v[24:25], v[4:5] op_sel_hi:[1,0]
	v_pk_mul_f32 v[22:23], v[22:23], v[4:5] op_sel_hi:[1,0]
	v_pk_mul_f32 v[20:21], v[20:21], v[4:5] op_sel_hi:[1,0]
	v_pk_mul_f32 v[18:19], v[18:19], v[4:5] op_sel_hi:[1,0]
	v_pk_mul_f32 v[16:17], v[16:17], v[4:5] op_sel_hi:[1,0]
	v_pk_mul_f32 v[46:47], v[46:47], v[4:5] op_sel_hi:[1,0]
	v_pk_mul_f32 v[44:45], v[44:45], v[4:5] op_sel_hi:[1,0]
	v_pk_mul_f32 v[42:43], v[42:43], v[4:5] op_sel_hi:[1,0]
	v_pk_mul_f32 v[40:41], v[40:41], v[4:5] op_sel_hi:[1,0]
	v_pk_mul_f32 v[38:39], v[38:39], v[4:5] op_sel_hi:[1,0]
	v_pk_mul_f32 v[36:37], v[36:37], v[4:5] op_sel_hi:[1,0]
	v_pk_mul_f32 v[34:35], v[34:35], v[4:5] op_sel_hi:[1,0]
	v_pk_mul_f32 v[32:33], v[32:33], v[4:5] op_sel_hi:[1,0]
	v_mov_b32_e32 v4, v0
.LBB0_982:
	v_fma_f32 v1, v48, s51, -v0
	v_exp_f32_e32 v1, v1
	v_fma_f32 v3, v49, s51, -v0
	v_exp_f32_e32 v3, v3
	v_fma_f32 v5, v50, s51, -v0
	v_exp_f32_e32 v5, v5
	v_fma_f32 v7, v51, s51, -v0
	v_exp_f32_e32 v7, v7
	v_fma_f32 v8, v52, s51, -v0
	v_add_f32_e32 v6, 0, v1
	v_exp_f32_e32 v8, v8
	v_fma_f32 v9, v53, s51, -v0
	v_add_f32_e32 v6, v3, v6
	v_exp_f32_e32 v9, v9
	v_fma_f32 v10, v54, s51, -v0
	v_add_f32_e32 v6, v5, v6
	v_exp_f32_e32 v10, v10
	v_fma_f32 v11, v55, s51, -v0
	v_add_f32_e32 v6, v7, v6
	v_exp_f32_e32 v11, v11
	v_fma_f32 v12, v56, s51, -v0
	v_add_f32_e32 v6, v8, v6
	v_exp_f32_e32 v12, v12
	v_fma_f32 v13, v57, s51, -v0
	v_add_f32_e32 v6, v9, v6
	v_exp_f32_e32 v13, v13
	v_add_f32_e32 v6, v10, v6
	v_add_f32_e32 v6, v11, v6
	v_add_f32_e32 v6, v12, v6
	v_add_f32_e32 v14, v13, v6
	v_fma_f32 v6, v58, s51, -v0
	v_exp_f32_e32 v15, v6
	v_cvt_pk_bf16_f32 v6, v1, v3
	v_cvt_pk_bf16_f32 v7, v5, v7
	v_cvt_pk_bf16_f32 v8, v8, v9
	v_cvt_pk_bf16_f32 v9, v10, v11
	v_fma_f32 v1, v59, s51, -v0
	v_fma_f32 v3, v60, s51, -v0
	v_mfma_f32_32x32x16_bf16 v[16:31], v[104:107], v[6:9], v[16:31]
	v_fma_f32 v5, v61, s51, -v0
	v_fma_f32 v10, v62, s51, -v0
	v_fma_f32 v0, v63, s51, -v0
	v_exp_f32_e32 v1, v1
	v_exp_f32_e32 v3, v3
	v_exp_f32_e32 v5, v5
	v_exp_f32_e32 v10, v10
	s_waitcnt vmcnt(17)
	v_mfma_f32_32x32x16_bf16 v[32:47], v[120:123], v[6:9], v[32:47]
	v_exp_f32_e32 v0, v0
	v_cvt_pk_bf16_f32 v6, v12, v13
	v_cvt_pk_bf16_f32 v7, v15, v1
	v_cvt_pk_bf16_f32 v8, v3, v5
	v_cvt_pk_bf16_f32 v9, v10, v0
	v_add_f32_e32 v11, v15, v14
	v_add_f32_e32 v1, v1, v11
	v_mfma_f32_32x32x16_bf16 v[16:31], v[108:111], v[6:9], v[16:31]
	v_add_f32_e32 v1, v3, v1
	v_add_f32_e32 v1, v5, v1
	v_add_f32_e32 v1, v10, v1
	v_add_f32_e32 v0, v0, v1
	v_add_f32_e32 v209, v0, v201
	v_mov_b32_e32 v205, v4
	s_nop 5
	v_mov_b64_e32 v[62:63], v[30:31]
	s_waitcnt vmcnt(16)
	v_mfma_f32_32x32x16_bf16 v[32:47], v[128:131], v[6:9], v[32:47]
	v_mov_b64_e32 v[60:61], v[28:29]
	v_mov_b64_e32 v[58:59], v[26:27]
	v_mov_b64_e32 v[56:57], v[24:25]
	v_mov_b64_e32 v[54:55], v[22:23]
	v_mov_b64_e32 v[52:53], v[20:21]
	v_mov_b64_e32 v[50:51], v[18:19]
	v_mov_b64_e32 v[48:49], v[16:17]
	s_nop 4
	v_mov_b64_e32 v[78:79], v[46:47]
	v_mov_b64_e32 v[76:77], v[44:45]
	v_mov_b64_e32 v[74:75], v[42:43]
	v_mov_b64_e32 v[72:73], v[40:41]
	v_mov_b64_e32 v[70:71], v[38:39]
	v_mov_b64_e32 v[68:69], v[36:37]
	v_mov_b64_e32 v[66:67], v[34:35]
	v_mov_b64_e32 v[64:65], v[32:33]
	s_cmp_gt_u32 s62, 28
	s_branch .LBB0_913

.LBB0_984:
	s_waitcnt vmcnt(23)
	v_mfma_f32_32x32x16_bf16 v[4:19], v[124:127], v[80:83], 0
	s_waitcnt vmcnt(21)
	v_mfma_f32_32x32x16_bf16 v[4:19], v[136:139], v[84:87], v[4:19]
	s_waitcnt vmcnt(19)
	v_mfma_f32_32x32x16_bf16 v[4:19], v[144:147], v[88:91], v[4:19]
	s_waitcnt vmcnt(18)
	v_mfma_f32_32x32x16_bf16 v[4:19], v[148:151], v[92:95], v[4:19]
	s_nop 11
	v_max_f32_e32 v0, v5, v5
	v_max_f32_e32 v1, v4, v4
	v_max_f32_e32 v0, v1, v0
	v_max3_f32 v0, v0, v6, v7
	v_max3_f32 v0, v0, v8, v9
	v_max3_f32 v0, v0, v10, v11
	v_max3_f32 v0, v0, v12, v13
	v_max3_f32 v0, v0, v14, v15
	v_max3_f32 v0, v0, v16, v17
	v_max3_f32 v0, v0, v18, v19
	v_mul_f32_e32 v0, 0x3e38aa3b, v0
	ds_bpermute_b32 v1, v224, v0
	s_waitcnt lgkmcnt(0)
	v_max3_f32 v0, v205, v0, v1
	v_cmp_gt_f32_e32 vcc, v0, v205
	s_cbranch_vccz .LBB0_986
	v_sub_f32_e32 v1, v205, v0
	v_exp_f32_e32 v20, v1
	v_mov_b32_e32 v205, v0
	v_mul_f32_e32 v209, v209, v20
	v_pk_mul_f32 v[62:63], v[62:63], v[20:21] op_sel_hi:[1,0]
	v_pk_mul_f32 v[60:61], v[60:61], v[20:21] op_sel_hi:[1,0]
	v_pk_mul_f32 v[58:59], v[58:59], v[20:21] op_sel_hi:[1,0]
	v_pk_mul_f32 v[56:57], v[56:57], v[20:21] op_sel_hi:[1,0]
	v_pk_mul_f32 v[54:55], v[54:55], v[20:21] op_sel_hi:[1,0]
	v_pk_mul_f32 v[52:53], v[52:53], v[20:21] op_sel_hi:[1,0]
	v_pk_mul_f32 v[50:51], v[50:51], v[20:21] op_sel_hi:[1,0]
	v_pk_mul_f32 v[48:49], v[48:49], v[20:21] op_sel_hi:[1,0]
	v_pk_mul_f32 v[78:79], v[78:79], v[20:21] op_sel_hi:[1,0]
	v_pk_mul_f32 v[76:77], v[76:77], v[20:21] op_sel_hi:[1,0]
	v_pk_mul_f32 v[74:75], v[74:75], v[20:21] op_sel_hi:[1,0]
	v_pk_mul_f32 v[72:73], v[72:73], v[20:21] op_sel_hi:[1,0]
	v_pk_mul_f32 v[70:71], v[70:71], v[20:21] op_sel_hi:[1,0]
	v_pk_mul_f32 v[68:69], v[68:69], v[20:21] op_sel_hi:[1,0]
	v_pk_mul_f32 v[66:67], v[66:67], v[20:21] op_sel_hi:[1,0]
	v_pk_mul_f32 v[64:65], v[64:65], v[20:21] op_sel_hi:[1,0]
.LBB0_986:
	v_fma_f32 v1, v4, s51, -v0
	v_exp_f32_e32 v1, v1
	v_fma_f32 v3, v5, s51, -v0
	v_exp_f32_e32 v3, v3
	v_fma_f32 v4, v6, s51, -v0
	v_exp_f32_e32 v6, v4
	v_fma_f32 v4, v7, s51, -v0
	v_add_f32_e32 v5, 0, v1
	v_exp_f32_e32 v7, v4
	v_fma_f32 v4, v8, s51, -v0
	v_add_f32_e32 v5, v3, v5
	v_exp_f32_e32 v8, v4
	v_fma_f32 v4, v9, s51, -v0
	v_exp_f32_e32 v9, v4
	v_add_f32_e32 v4, v6, v5
	v_fma_f32 v5, v10, s51, -v0
	v_exp_f32_e32 v10, v5
	v_fma_f32 v5, v11, s51, -v0
	v_add_f32_e32 v4, v7, v4
	v_exp_f32_e32 v11, v5
	v_fma_f32 v5, v12, s51, -v0
	v_add_f32_e32 v4, v8, v4
	v_exp_f32_e32 v12, v5
	v_fma_f32 v5, v13, s51, -v0
	v_add_f32_e32 v4, v9, v4
	v_exp_f32_e32 v13, v5
	v_add_f32_e32 v4, v10, v4
	v_add_f32_e32 v4, v11, v4
	v_add_f32_e32 v4, v12, v4
	v_add_f32_e32 v20, v13, v4
	v_fma_f32 v4, v14, s51, -v0
	v_exp_f32_e32 v14, v4
	v_cvt_pk_bf16_f32 v4, v1, v3
	v_cvt_pk_bf16_f32 v5, v6, v7
	v_cvt_pk_bf16_f32 v6, v8, v9
	v_cvt_pk_bf16_f32 v7, v10, v11
	v_fma_f32 v1, v15, s51, -v0
	v_fma_f32 v3, v16, s51, -v0
	v_mfma_f32_32x32x16_bf16 v[48:63], v[132:135], v[4:7], v[48:63]
	v_fma_f32 v8, v17, s51, -v0
	v_fma_f32 v9, v18, s51, -v0
	v_fma_f32 v0, v19, s51, -v0
	v_exp_f32_e32 v1, v1
	v_exp_f32_e32 v3, v3
	v_exp_f32_e32 v8, v8
	v_exp_f32_e32 v9, v9
	s_waitcnt vmcnt(17)
	v_mfma_f32_32x32x16_bf16 v[64:79], v[152:155], v[4:7], v[64:79]
	v_exp_f32_e32 v0, v0
	v_cvt_pk_bf16_f32 v4, v12, v13
	v_cvt_pk_bf16_f32 v5, v14, v1
	v_cvt_pk_bf16_f32 v6, v3, v8
	v_cvt_pk_bf16_f32 v7, v9, v0
	v_add_f32_e32 v10, v14, v20
	v_add_f32_e32 v1, v1, v10
	v_mfma_f32_32x32x16_bf16 v[48:63], v[140:143], v[4:7], v[48:63]
	v_add_f32_e32 v1, v3, v1
	v_add_f32_e32 v1, v8, v1
	v_add_f32_e32 v1, v9, v1
	v_add_f32_e32 v0, v0, v1
	v_add_f32_e32 v201, v0, v209
	s_nop 6
	v_mov_b64_e32 v[16:17], v[48:49]
	s_waitcnt vmcnt(16)
	v_mfma_f32_32x32x16_bf16 v[64:79], v[156:159], v[4:7], v[64:79]
	v_mov_b64_e32 v[18:19], v[50:51]
	v_mov_b64_e32 v[20:21], v[52:53]
	v_mov_b64_e32 v[22:23], v[54:55]
	v_mov_b64_e32 v[24:25], v[56:57]
	v_mov_b64_e32 v[26:27], v[58:59]
	v_mov_b64_e32 v[28:29], v[60:61]
	v_mov_b64_e32 v[30:31], v[62:63]
	s_nop 4
	v_mov_b64_e32 v[32:33], v[64:65]
	v_mov_b64_e32 v[34:35], v[66:67]
	v_mov_b64_e32 v[36:37], v[68:69]
	v_mov_b64_e32 v[38:39], v[70:71]
	v_mov_b64_e32 v[40:41], v[72:73]
	v_mov_b64_e32 v[42:43], v[74:75]
	v_mov_b64_e32 v[44:45], v[76:77]
	v_mov_b64_e32 v[46:47], v[78:79]
	v_mov_b32_e32 v4, v205
	s_cmp_gt_u32 s62, 27
	s_branch .LBB0_978

.LBB0_988:
	s_cmp_gt_u32 s62, 13
	s_mov_b64 s[10:11], -1
	s_cbranch_scc0 .LBB0_1051
	s_sub_i32 s10, s20, 18
	s_lshr_b32 s10, s10, 1
	s_and_b32 s11, s62, 1
	s_add_i32 s10, s10, s60
	v_lshl_or_b32 v0, s11, 5, v198
	s_mulk_i32 s10, 0x7c
	s_add_i32 s10, s15, s10
	v_sub_u32_e32 v1, v0, v193
	v_lshl_add_u32 v5, v1, 2, s10
	s_cmp_lg_u32 s11, s47
	v_sub_u32_e32 v6, v0, v223
	s_mov_b64 s[10:11], -1
	s_cbranch_scc0 .LBB0_1014
	s_and_b64 vcc, exec, s[6:7]
	s_cbranch_vccz .LBB0_1002
	s_waitcnt vmcnt(23)
	v_mfma_f32_32x32x16_bf16 v[48:63], v[160:163], v[80:83], 0
	v_add_u32_e32 v0, 24, v6
	v_cmp_gt_u32_e32 vcc, 16, v0
	v_mov_b32_e32 v0, 0xf149f2ca
	v_mov_b32_e32 v1, 0xf149f2ca
	s_waitcnt vmcnt(22)
	v_mfma_f32_32x32x16_bf16 v[48:63], v[164:167], v[84:87], v[48:63]
	s_waitcnt vmcnt(19)
	v_mfma_f32_32x32x16_bf16 v[48:63], v[168:171], v[88:91], v[48:63]
	s_waitcnt vmcnt(18)
	v_mfma_f32_32x32x16_bf16 v[48:63], v[180:183], v[92:95], v[48:63]
	s_and_saveexec_b64 s[10:11], vcc
	s_cbranch_execz .LBB0_993
	ds_read_b32 v1, v5 offset:2048
	s_waitcnt lgkmcnt(0)
	s_nop 7
	v_fmac_f32_e32 v1, 0x3e38aa3b, v60

.LBB0_1001:
	v_sub_f32_e32 v1, v1, v9
	v_sub_f32_e32 v0, v0, v9
	v_exp_f32_e32 v1, v1
	v_exp_f32_e32 v0, v0
	v_sub_f32_e32 v7, v7, v9
	v_exp_f32_e32 v7, v7
	v_sub_f32_e32 v3, v3, v9
	v_exp_f32_e32 v3, v3
	v_cvt_pk_bf16_f32 v14, v1, v0
	v_add_f32_e32 v1, 0, v1
	v_add_f32_e32 v0, v0, v1
	v_add_f32_e32 v0, v7, v0
	v_cvt_pk_bf16_f32 v15, v7, v3
	v_mov_b32_e32 v12, v2
	v_mov_b32_e32 v13, v2
	v_add_f32_e32 v0, v3, v0
	v_add_f32_e32 v7, v0, v8
	v_mfma_f32_32x32x16_bf16 v[48:63], v[176:179], v[12:15], v[48:63]
	s_mov_b64 s[10:11], 0
	s_waitcnt vmcnt(16)
	v_mfma_f32_32x32x16_bf16 v[64:79], v[188:191], v[12:15], v[64:79]
.LBB0_1002:
	s_and_b64 vcc, exec, s[10:11]
	s_cbranch_vccz .LBB0_1056
	s_waitcnt vmcnt(23)
	v_mfma_f32_32x32x16_bf16 v[48:63], v[160:163], v[80:83], 0
	v_cmp_gt_u32_e32 vcc, 16, v6
	v_mov_b32_e32 v1, 0xf149f2ca
	v_mov_b32_e32 v0, 0xf149f2ca
	s_waitcnt vmcnt(22)
	v_mfma_f32_32x32x16_bf16 v[48:63], v[164:167], v[84:87], v[48:63]
	s_waitcnt vmcnt(19)
	v_mfma_f32_32x32x16_bf16 v[48:63], v[168:171], v[88:91], v[48:63]
	s_waitcnt vmcnt(18)
	v_mfma_f32_32x32x16_bf16 v[48:63], v[180:183], v[92:95], v[48:63]
	s_and_saveexec_b64 s[10:11], vcc
	s_cbranch_execz .LBB0_1005
	ds_read_b32 v0, v5 offset:1952
	s_waitcnt lgkmcnt(0)
	s_nop 7
	v_fmac_f32_e32 v0, 0x3e38aa3b, v48

.LBB0_1013:
	v_sub_f32_e32 v1, v1, v9
	v_sub_f32_e32 v0, v0, v9
	v_sub_f32_e32 v7, v7, v9
	v_sub_f32_e32 v3, v3, v9
	v_exp_f32_e32 v11, v1
	v_exp_f32_e32 v9, v0
	v_exp_f32_e32 v12, v3
	v_exp_f32_e32 v7, v7
	v_mov_b32_e32 v3, v2
	v_cvt_pk_bf16_f32 v0, v9, v11
	v_add_f32_e32 v9, 0, v9
	v_add_f32_e32 v9, v11, v9
	v_add_f32_e32 v9, v12, v9
	v_cvt_pk_bf16_f32 v1, v12, v7
	v_add_f32_e32 v7, v7, v9
	v_add_f32_e32 v7, v7, v8
	v_mfma_f32_32x32x16_bf16 v[48:63], v[172:175], v[0:3], v[48:63]
	s_mov_b64 s[10:11], 0
	s_waitcnt vmcnt(17)
	v_mfma_f32_32x32x16_bf16 v[64:79], v[184:187], v[0:3], v[64:79]

.LBB0_1015:
	s_waitcnt vmcnt(23)
	v_mfma_f32_32x32x16_bf16 v[48:63], v[160:163], v[80:83], 0
	v_cmp_gt_u32_e32 vcc, 16, v6
	v_mov_b32_e32 v0, 0xf149f2ca
	v_mov_b32_e32 v1, 0xf149f2ca
	s_waitcnt vmcnt(22)
	v_mfma_f32_32x32x16_bf16 v[48:63], v[164:167], v[84:87], v[48:63]
	s_waitcnt vmcnt(19)
	v_mfma_f32_32x32x16_bf16 v[48:63], v[168:171], v[88:91], v[48:63]
	s_waitcnt vmcnt(18)
	v_mfma_f32_32x32x16_bf16 v[48:63], v[180:183], v[92:95], v[48:63]
	s_and_saveexec_b64 s[10:11], vcc
	s_cbranch_execz .LBB0_1017
	ds_read_b32 v1, v5 offset:1952
	s_waitcnt lgkmcnt(0)
	s_nop 7
	v_fmac_f32_e32 v1, 0x3e38aa3b, v48

.LBB0_1049:
	v_sub_f32_e32 v1, v1, v6
	v_exp_f32_e32 v1, v1
	v_sub_f32_e32 v0, v0, v6
	v_exp_f32_e32 v0, v0
	v_sub_f32_e32 v7, v7, v6
	v_exp_f32_e32 v7, v7
	v_sub_f32_e32 v3, v3, v6
	v_exp_f32_e32 v3, v3
	v_sub_f32_e32 v9, v9, v6
	v_add_f32_e32 v228, 0, v1
	v_exp_f32_e32 v9, v9
	v_sub_f32_e32 v8, v8, v6
	v_add_f32_e32 v228, v0, v228
	v_exp_f32_e32 v8, v8
	v_sub_f32_e32 v12, v12, v6
	v_add_f32_e32 v228, v7, v228
	v_exp_f32_e32 v12, v12
	v_sub_f32_e32 v11, v11, v6
	v_add_f32_e32 v228, v3, v228
	v_exp_f32_e32 v11, v11
	v_sub_f32_e32 v15, v15, v6
	v_add_f32_e32 v228, v9, v228
	v_exp_f32_e32 v15, v15
	v_sub_f32_e32 v14, v14, v6
	v_add_f32_e32 v228, v8, v228
	v_exp_f32_e32 v14, v14
	v_add_f32_e32 v228, v12, v228
	v_add_f32_e32 v228, v11, v228
	v_add_f32_e32 v228, v15, v228
	v_add_f32_e32 v232, v14, v228
	v_cvt_pk_bf16_f32 v228, v1, v0
	v_cvt_pk_bf16_f32 v229, v7, v3
	v_cvt_pk_bf16_f32 v230, v9, v8
	v_cvt_pk_bf16_f32 v231, v12, v11
	v_sub_f32_e32 v213, v213, v6
	v_sub_f32_e32 v0, v13, v6
	v_mfma_f32_32x32x16_bf16 v[48:63], v[172:175], v[228:231], v[48:63]
	v_sub_f32_e32 v1, v209, v6
	v_sub_f32_e32 v3, v205, v6
	v_sub_f32_e32 v7, v227, v6
	v_sub_f32_e32 v6, v226, v6
	v_exp_f32_e32 v213, v213
	v_exp_f32_e32 v0, v0
	v_exp_f32_e32 v1, v1
	s_waitcnt vmcnt(17)
	v_mfma_f32_32x32x16_bf16 v[64:79], v[184:187], v[228:231], v[64:79]
	v_exp_f32_e32 v3, v3
	v_exp_f32_e32 v7, v7
	v_exp_f32_e32 v6, v6
	v_cvt_pk_bf16_f32 v12, v15, v14
	v_cvt_pk_bf16_f32 v13, v213, v0
	v_cvt_pk_bf16_f32 v14, v1, v3
	v_cvt_pk_bf16_f32 v15, v7, v6
	v_add_f32_e32 v8, v213, v232
	v_add_f32_e32 v0, v0, v8
	v_mfma_f32_32x32x16_bf16 v[48:63], v[176:179], v[12:15], v[48:63]
	v_add_f32_e32 v0, v1, v0
	v_add_f32_e32 v0, v3, v0
	v_add_f32_e32 v0, v7, v0
	v_add_f32_e32 v0, v6, v0
	v_add_f32_e32 v7, v0, v5
	s_waitcnt vmcnt(16)
	v_mfma_f32_32x32x16_bf16 v[64:79], v[188:191], v[12:15], v[64:79]

.LBB0_1051:
	s_andn2_b64 vcc, exec, s[10:11]
	s_cbranch_vccnz .LBB0_845
	s_waitcnt vmcnt(23)
	v_mfma_f32_32x32x16_bf16 v[48:63], v[160:163], v[80:83], 0
	s_waitcnt vmcnt(22)
	v_mfma_f32_32x32x16_bf16 v[48:63], v[164:167], v[84:87], v[48:63]
	s_waitcnt vmcnt(19)
	v_mfma_f32_32x32x16_bf16 v[48:63], v[168:171], v[88:91], v[48:63]
	s_waitcnt vmcnt(18)
	v_mfma_f32_32x32x16_bf16 v[48:63], v[180:183], v[92:95], v[48:63]
	s_nop 11
	v_max_f32_e32 v0, v49, v49
	v_max_f32_e32 v1, v48, v48
	v_max_f32_e32 v0, v1, v0
	v_max3_f32 v0, v0, v50, v51
	v_max3_f32 v0, v0, v52, v53
	v_max3_f32 v0, v0, v54, v55
	v_max3_f32 v0, v0, v56, v57
	v_max3_f32 v0, v0, v58, v59
	v_max3_f32 v0, v0, v60, v61
	v_max3_f32 v0, v0, v62, v63
	v_mul_f32_e32 v0, 0x3e38aa3b, v0
	ds_bpermute_b32 v1, v224, v0
	s_waitcnt lgkmcnt(0)
	v_max3_f32 v0, v4, v0, v1
	v_cmp_gt_f32_e32 vcc, v0, v4
	s_cbranch_vccz .LBB0_844
	v_sub_f32_e32 v1, v4, v0
	v_exp_f32_e32 v4, v1
	s_nop 0
	v_mul_f32_e32 v201, v201, v4
	v_pk_mul_f32 v[30:31], v[30:31], v[4:5] op_sel_hi:[1,0]
	v_pk_mul_f32 v[28:29], v[28:29], v[4:5] op_sel_hi:[1,0]
	v_pk_mul_f32 v[26:27], v[26:27], v[4:5] op_sel_hi:[1,0]
	v_pk_mul_f32 v[24:25], v[24:25], v[4:5] op_sel_hi:[1,0]
	v_pk_mul_f32 v[22:23], v[22:23], v[4:5] op_sel_hi:[1,0]
	v_pk_mul_f32 v[20:21], v[20:21], v[4:5] op_sel_hi:[1,0]
	v_pk_mul_f32 v[18:19], v[18:19], v[4:5] op_sel_hi:[1,0]
	v_pk_mul_f32 v[16:17], v[16:17], v[4:5] op_sel_hi:[1,0]
	v_pk_mul_f32 v[46:47], v[46:47], v[4:5] op_sel_hi:[1,0]
	v_pk_mul_f32 v[44:45], v[44:45], v[4:5] op_sel_hi:[1,0]
	v_pk_mul_f32 v[42:43], v[42:43], v[4:5] op_sel_hi:[1,0]
	v_pk_mul_f32 v[40:41], v[40:41], v[4:5] op_sel_hi:[1,0]
	v_pk_mul_f32 v[38:39], v[38:39], v[4:5] op_sel_hi:[1,0]
	v_pk_mul_f32 v[36:37], v[36:37], v[4:5] op_sel_hi:[1,0]
	v_pk_mul_f32 v[34:35], v[34:35], v[4:5] op_sel_hi:[1,0]
	v_pk_mul_f32 v[32:33], v[32:33], v[4:5] op_sel_hi:[1,0]
	v_mov_b32_e32 v4, v0
	s_branch .LBB0_844
